# E50: E49 with the conversion jobs ordered n-tile fastest (contiguous source rows across concurrent work-groups)
# speedup vs baseline: 1.0019x; 1.0019x over previous
; __device__ __forceinline__ int tid_() { int t = threadIdx.x; asm volatile("" : "+v"(t)); return t; }
; __device__ __forceinline__ void conv_matrix(const float* __restrict__ src, int K, int N, int Npad, bf16_t* __restrict__ dst, const float* __restrict__ scale, float* tile) {
;   const int nk = K / 64, nn = Npad / 64, tot = nk * nn;
;   const int tid = tid_(), tx = tid & 63, ty = tid >> 6, nl = tid >> 3, ks = (tid & 7) * 8;
;   for (int i0 = blockIdx.x; i0 < tot; i0 += 2 * gridDim.x) {
;     const int i1 = i0 + gridDim.x; const bool has1 = i1 < tot;
;     const int k0a = (i0 % nk) * 64, n0a = (i0 / nk) * 64, k0b = has1 ? (i1 % nk) * 64 : 0, n0b = has1 ? (i1 / nk) * 64 : 0;
;     float va[8], vb[8];
; #pragma unroll
;     for (int i = 0; i < 8; ++i) { const int k = k0a + ty + 8 * i, n = n0a + tx; float v = (n < N) ? src[(size_t)k * N + n] : 0.f; if (scale) v *= scale[k]; va[i] = v; }
;     if (has1) {
; #pragma unroll
;       for (int i = 0; i < 8; ++i) { const int k = k0b + ty + 8 * i, n = n0b + tx; float v = (n < N) ? src[(size_t)k * N + n] : 0.f; if (scale) v *= scale[k]; vb[i] = v; }
;     }
.LBB0_1028:
	s_cmp_lt_u32 s2, 12
	s_cbranch_scc1 .Lcvo_skip
	v_writelane_b32 v255, s4, 46
	v_writelane_b32 v255, s5, 47
	v_writelane_b32 v255, s10, 48
	v_writelane_b32 v255, s11, 49
	v_writelane_b32 v255, s12, 50
	v_writelane_b32 v255, s13, 51
	v_writelane_b32 v255, s14, 52
	v_writelane_b32 v255, s15, 53
	v_writelane_b32 v255, s20, 54
	v_writelane_b32 v255, s21, 55
	v_writelane_b32 v255, s22, 56
	v_writelane_b32 v255, s23, 57
	v_writelane_b32 v255, s24, 58
	v_writelane_b32 v255, s25, 59
	v_writelane_b32 v255, s26, 60
	v_writelane_b32 v255, s27, 61
	s_load_dwordx2 s[10:11], s[0:1], 0x40
	s_load_dwordx2 s[12:13], s[0:1], 0x48
	s_load_dwordx2 s[14:15], s[0:1], 0xd8
	v_and_b32_e32 v1, 63, v187
	v_lshrrev_b32_e32 v7, 6, v187
	v_lshrrev_b32_e32 v4, 3, v187
	v_and_b32_e32 v5, 7, v187
	s_nop 1
	v_readfirstlane_b32 s6, v7
	v_readlane_b32 s7, v255, 32
	v_mul_u32_u24_e32 v2, 0x41, v7
	v_add_u32_e32 v2, v2, v1
	v_lshlrev_b32_e32 v2, 2, v2
	v_add_u32_e32 v2, 16, v2
	v_lshlrev_b32_e32 v1, 2, v1
	v_mul_u32_u24_e32 v3, 0x208, v5
	v_add_u32_e32 v3, v3, v4
	v_lshlrev_b32_e32 v3, 2, v3
	v_add_u32_e32 v3, 16, v3
	v_lshlrev_b32_e32 v5, 4, v5
	s_lshl_b32 s7, s7, 24
	s_waitcnt lgkmcnt(0)
	s_add_u32 s10, s10, s7
	s_addc_u32 s11, s11, 0
	s_add_u32 s12, s12, s7
	s_addc_u32 s13, s13, 0
	s_sub_u32 s4, s2, 12
	s_cmp_lt_u32 s4, 0x400
	s_cselect_b32 s20, 6, 4
	s_cselect_b32 s21, 14, 12
	s_cselect_b32 s26, s10, s12
	s_cselect_b32 s27, s11, s13
	s_and_b32 s22, s4, 0x3ff
	s_lshl_b32 s25, 1, s20
	s_sub_u32 s25, s25, 1
	s_and_b32 s24, s22, s25
	s_lshr_b32 s23, s22, s20
	s_lshl_b32 s23, s23, 6
	s_add_u32 s23, s23, s6
	s_lshl_b32 s23, s23, s21
	s_lshl_b32 s24, s24, 8
	s_add_u32 s23, s23, s24
	s_add_u32 s26, s26, s23
	s_addc_u32 s27, s27, 0
	s_add_u32 s25, s21, 3
	s_lshl_b32 s25, 1, s25
	v_add_u32_e32 v21, s25, v1
	v_add_u32_e32 v22, s25, v21
	v_add_u32_e32 v23, s25, v22
	v_add_u32_e32 v24, s25, v23
	v_add_u32_e32 v25, s25, v24
	v_add_u32_e32 v26, s25, v25
	v_add_u32_e32 v27, s25, v26
	global_load_dword v30, v1, s[26:27]
	global_load_dword v31, v21, s[26:27]
	global_load_dword v32, v22, s[26:27]
	global_load_dword v33, v23, s[26:27]
	global_load_dword v34, v24, s[26:27]
	global_load_dword v35, v25, s[26:27]
	global_load_dword v36, v26, s[26:27]
	global_load_dword v37, v27, s[26:27]
	s_add_u32 s5, s4, 244
	s_cmp_lt_u32 s5, 0x400
	s_cselect_b32 s20, 6, 4
	s_cselect_b32 s21, 14, 12
	s_cselect_b32 s26, s10, s12
	s_cselect_b32 s27, s11, s13
	s_and_b32 s22, s5, 0x3ff
	s_lshl_b32 s25, 1, s20
	s_sub_u32 s25, s25, 1
	s_and_b32 s24, s22, s25
	s_lshr_b32 s23, s22, s20
	s_lshl_b32 s23, s23, 6
	s_add_u32 s23, s23, s6
	s_lshl_b32 s23, s23, s21
	s_lshl_b32 s24, s24, 8
	s_add_u32 s23, s23, s24
	s_add_u32 s26, s26, s23
	s_addc_u32 s27, s27, 0
	s_add_u32 s25, s21, 3
	s_lshl_b32 s25, 1, s25
	v_add_u32_e32 v21, s25, v1
	v_add_u32_e32 v22, s25, v21
	v_add_u32_e32 v23, s25, v22
	v_add_u32_e32 v24, s25, v23
	v_add_u32_e32 v25, s25, v24
	v_add_u32_e32 v26, s25, v25
	v_add_u32_e32 v27, s25, v26
	global_load_dword v40, v1, s[26:27]
	global_load_dword v41, v21, s[26:27]
	global_load_dword v42, v22, s[26:27]
	global_load_dword v43, v23, s[26:27]
	global_load_dword v44, v24, s[26:27]
	global_load_dword v45, v25, s[26:27]
	global_load_dword v46, v26, s[26:27]
	global_load_dword v47, v27, s[26:27]
	s_mov_b32 s7, 0
.Lcvo_j0:
	s_add_u32 s5, s4, 488
	s_cmp_lt_u32 s5, 0x800
	s_cbranch_scc0 .Lcvo_t0
	s_cmp_lt_u32 s5, 0x400
	s_cselect_b32 s20, 6, 4
	s_cselect_b32 s21, 14, 12
	s_cselect_b32 s26, s10, s12
	s_cselect_b32 s27, s11, s13
	s_and_b32 s22, s5, 0x3ff
	s_lshl_b32 s25, 1, s20
	s_sub_u32 s25, s25, 1
	s_and_b32 s24, s22, s25
	s_lshr_b32 s23, s22, s20
	s_lshl_b32 s23, s23, 6
	s_add_u32 s23, s23, s6
	s_lshl_b32 s23, s23, s21
	s_lshl_b32 s24, s24, 8
	s_add_u32 s23, s23, s24
	s_add_u32 s26, s26, s23
	s_addc_u32 s27, s27, 0
	s_add_u32 s25, s21, 3
	s_lshl_b32 s25, 1, s25
	v_add_u32_e32 v21, s25, v1
	v_add_u32_e32 v22, s25, v21
	v_add_u32_e32 v23, s25, v22
	v_add_u32_e32 v24, s25, v23
	v_add_u32_e32 v25, s25, v24
	v_add_u32_e32 v26, s25, v25
	v_add_u32_e32 v27, s25, v26
	global_load_dword v8, v1, s[26:27]
	global_load_dword v9, v21, s[26:27]
	global_load_dword v10, v22, s[26:27]
	global_load_dword v11, v23, s[26:27]
	global_load_dword v12, v24, s[26:27]
	global_load_dword v13, v25, s[26:27]
	global_load_dword v14, v26, s[26:27]
	global_load_dword v15, v27, s[26:27]
	s_cmp_lt_u32 s7, 2
	s_cbranch_scc1 .Lcvo_w0
	s_waitcnt vmcnt(18)
	s_branch .Lcvo_p0

; __device__ __forceinline__ unsigned cvt_pk_bf16(float lo, float hi) { unsigned r; asm volatile("v_cvt_pk_bf16_f32 %0, %1, %2" : "=v"(r) : "v"(lo), "v"(hi)); return r; }
; __device__ __forceinline__ void conv_matrix(const float* __restrict__ src, int K, int N, int Npad, bf16_t* __restrict__ dst, const float* __restrict__ scale, float* tile) {
;     ...
;   for (int i0 = blockIdx.x; i0 < tot; i0 += 2 * gridDim.x) {
;     const int i1 = i0 + gridDim.x; const bool has1 = i1 < tot;
;     const int k0a = (i0 % nk) * 64, n0a = (i0 / nk) * 64, k0b = has1 ? (i1 % nk) * 64 : 0, n0b = has1 ? (i1 / nk) * 64 : 0;
;     float va[8], vb[8];
; #pragma unroll
;     for (int i = 0; i < 8; ++i) { const int k = k0a + ty + 8 * i, n = n0a + tx; float v = (n < N) ? src[(size_t)k * N + n] : 0.f; if (scale) v *= scale[k]; va[i] = v; }
;     if (has1) {
; #pragma unroll
;       for (int i = 0; i < 8; ++i) { const int k = k0b + ty + 8 * i, n = n0b + tx; float v = (n < N) ? src[(size_t)k * N + n] : 0.f; if (scale) v *= scale[k]; vb[i] = v; }
;     }
;     __syncthreads();
; #pragma unroll
;     for (int i = 0; i < 8; ++i) { tile[(ty + 8 * i) * 65 + tx] = va[i]; if (has1) tile[4160 + (ty + 8 * i) * 65 + tx] = vb[i]; }
;     __syncthreads();
;     { float v[8];
; #pragma unroll
;       for (int j = 0; j < 8; ++j) v[j] = tile[(ks + j) * 65 + nl];
;       u32x4 w = {cvt_pk_bf16(v[0], v[1]), cvt_pk_bf16(v[2], v[3]), cvt_pk_bf16(v[4], v[5]), cvt_pk_bf16(v[6], v[7])};
;       *(u32x4*)(dst + (size_t)(n0a + nl) * K + k0a + ks) = w; }
;     if (has1) { float v[8];
; #pragma unroll
;       for (int j = 0; j < 8; ++j) v[j] = tile[4160 + (ks + j) * 65 + nl];
;       u32x4 w = {cvt_pk_bf16(v[0], v[1]), cvt_pk_bf16(v[2], v[3]), cvt_pk_bf16(v[4], v[5]), cvt_pk_bf16(v[6], v[7])};
;       *(u32x4*)(dst + (size_t)(n0b + nl) * K + k0b + ks) = w; }
.Lcvo_p0:
	ds_write_b32 v2, v30 offset:0
	ds_write_b32 v2, v31 offset:2080
	ds_write_b32 v2, v32 offset:4160
	ds_write_b32 v2, v33 offset:6240
	ds_write_b32 v2, v34 offset:8320
	ds_write_b32 v2, v35 offset:10400
	ds_write_b32 v2, v36 offset:12480
	ds_write_b32 v2, v37 offset:14560
	s_cmp_lt_u32 s4, 0x400
	s_cselect_b32 s20, 6, 4
	s_cselect_b32 s21, 17, 19
	s_cselect_b32 s8, 11, 13
	s_mov_b32 s9, 0x9280000
	s_cselect_b32 s9, 0x8a80000, s9
	s_and_b32 s22, s4, 0x3ff
	s_lshl_b32 s25, 1, s20
	s_sub_u32 s25, s25, 1
	s_and_b32 s24, s22, s25
	s_lshr_b32 s23, s22, s20
	s_lshl_b32 s24, s24, s21
	s_lshl_b32 s23, s23, 7
	s_add_u32 s24, s24, s23
	s_add_u32 s24, s24, s9
	s_add_u32 s26, s14, s24
	s_addc_u32 s27, s15, 0
	v_lshlrev_b32_e32 v6, s8, v4
	v_add_u32_e32 v6, v6, v5
	s_waitcnt lgkmcnt(0)
	s_barrier
	ds_read_b32 v50, v3 offset:0
	ds_read_b32 v51, v3 offset:260
	ds_read_b32 v52, v3 offset:520
	ds_read_b32 v53, v3 offset:780
	ds_read_b32 v54, v3 offset:1040
	ds_read_b32 v55, v3 offset:1300
	ds_read_b32 v56, v3 offset:1560
	ds_read_b32 v57, v3 offset:1820
	s_waitcnt lgkmcnt(0)
	v_cvt_pk_bf16_f32 v60, v50, v51
	v_cvt_pk_bf16_f32 v61, v52, v53
	v_cvt_pk_bf16_f32 v62, v54, v55
	v_cvt_pk_bf16_f32 v63, v56, v57
	global_store_dwordx4 v6, v[60:63], s[26:27]
	s_add_u32 s7, s7, 1
	s_add_u32 s4, s4, 244
	s_cmp_lt_u32 s4, 0x800
	s_cbranch_scc0 .Lcvo_done
.Lcvo_j1:
	s_add_u32 s5, s4, 488
	s_cmp_lt_u32 s5, 0x800
	s_cbranch_scc0 .Lcvo_t1
	s_cmp_lt_u32 s5, 0x400
	s_cselect_b32 s20, 6, 4
	s_cselect_b32 s21, 14, 12
	s_cselect_b32 s26, s10, s12
	s_cselect_b32 s27, s11, s13
	s_and_b32 s22, s5, 0x3ff
	s_lshl_b32 s25, 1, s20
	s_sub_u32 s25, s25, 1
	s_and_b32 s24, s22, s25
	s_lshr_b32 s23, s22, s20
	s_lshl_b32 s23, s23, 6
	s_add_u32 s23, s23, s6
	s_lshl_b32 s23, s23, s21
	s_lshl_b32 s24, s24, 8
	s_add_u32 s23, s23, s24
	s_add_u32 s26, s26, s23
	s_addc_u32 s27, s27, 0
	s_add_u32 s25, s21, 3
	s_lshl_b32 s25, 1, s25
	v_add_u32_e32 v21, s25, v1
	v_add_u32_e32 v22, s25, v21
	v_add_u32_e32 v23, s25, v22
	v_add_u32_e32 v24, s25, v23
	v_add_u32_e32 v25, s25, v24
	v_add_u32_e32 v26, s25, v25
	v_add_u32_e32 v27, s25, v26
	global_load_dword v30, v1, s[26:27]
	global_load_dword v31, v21, s[26:27]
	global_load_dword v32, v22, s[26:27]
	global_load_dword v33, v23, s[26:27]
	global_load_dword v34, v24, s[26:27]
	global_load_dword v35, v25, s[26:27]
	global_load_dword v36, v26, s[26:27]
	global_load_dword v37, v27, s[26:27]
	s_cmp_lt_u32 s7, 2
	s_cbranch_scc1 .Lcvo_w1
	s_waitcnt vmcnt(18)
	s_branch .Lcvo_p1

; __device__ __forceinline__ unsigned cvt_pk_bf16(float lo, float hi) { unsigned r; asm volatile("v_cvt_pk_bf16_f32 %0, %1, %2" : "=v"(r) : "v"(lo), "v"(hi)); return r; }
; __device__ __forceinline__ void conv_matrix(const float* __restrict__ src, int K, int N, int Npad, bf16_t* __restrict__ dst, const float* __restrict__ scale, float* tile) {
;     ...
;   for (int i0 = blockIdx.x; i0 < tot; i0 += 2 * gridDim.x) {
;     const int i1 = i0 + gridDim.x; const bool has1 = i1 < tot;
;     const int k0a = (i0 % nk) * 64, n0a = (i0 / nk) * 64, k0b = has1 ? (i1 % nk) * 64 : 0, n0b = has1 ? (i1 / nk) * 64 : 0;
;     float va[8], vb[8];
; #pragma unroll
;     for (int i = 0; i < 8; ++i) { const int k = k0a + ty + 8 * i, n = n0a + tx; float v = (n < N) ? src[(size_t)k * N + n] : 0.f; if (scale) v *= scale[k]; va[i] = v; }
;     if (has1) {
; #pragma unroll
;       for (int i = 0; i < 8; ++i) { const int k = k0b + ty + 8 * i, n = n0b + tx; float v = (n < N) ? src[(size_t)k * N + n] : 0.f; if (scale) v *= scale[k]; vb[i] = v; }
;     }
;     __syncthreads();
; #pragma unroll
;     for (int i = 0; i < 8; ++i) { tile[(ty + 8 * i) * 65 + tx] = va[i]; if (has1) tile[4160 + (ty + 8 * i) * 65 + tx] = vb[i]; }
;     __syncthreads();
;     { float v[8];
; #pragma unroll
;       for (int j = 0; j < 8; ++j) v[j] = tile[(ks + j) * 65 + nl];
;       u32x4 w = {cvt_pk_bf16(v[0], v[1]), cvt_pk_bf16(v[2], v[3]), cvt_pk_bf16(v[4], v[5]), cvt_pk_bf16(v[6], v[7])};
;       *(u32x4*)(dst + (size_t)(n0a + nl) * K + k0a + ks) = w; }
;     if (has1) { float v[8];
; #pragma unroll
;       for (int j = 0; j < 8; ++j) v[j] = tile[4160 + (ks + j) * 65 + nl];
;       u32x4 w = {cvt_pk_bf16(v[0], v[1]), cvt_pk_bf16(v[2], v[3]), cvt_pk_bf16(v[4], v[5]), cvt_pk_bf16(v[6], v[7])};
;       *(u32x4*)(dst + (size_t)(n0b + nl) * K + k0b + ks) = w; }
.Lcvo_p1:
	ds_write_b32 v2, v40 offset:16640
	ds_write_b32 v2, v41 offset:18720
	ds_write_b32 v2, v42 offset:20800
	ds_write_b32 v2, v43 offset:22880
	ds_write_b32 v2, v44 offset:24960
	ds_write_b32 v2, v45 offset:27040
	ds_write_b32 v2, v46 offset:29120
	ds_write_b32 v2, v47 offset:31200
	s_cmp_lt_u32 s4, 0x400
	s_cselect_b32 s20, 6, 4
	s_cselect_b32 s21, 17, 19
	s_cselect_b32 s8, 11, 13
	s_mov_b32 s9, 0x9280000
	s_cselect_b32 s9, 0x8a80000, s9
	s_and_b32 s22, s4, 0x3ff
	s_lshl_b32 s25, 1, s20
	s_sub_u32 s25, s25, 1
	s_and_b32 s24, s22, s25
	s_lshr_b32 s23, s22, s20
	s_lshl_b32 s24, s24, s21
	s_lshl_b32 s23, s23, 7
	s_add_u32 s24, s24, s23
	s_add_u32 s24, s24, s9
	s_add_u32 s26, s14, s24
	s_addc_u32 s27, s15, 0
	v_lshlrev_b32_e32 v6, s8, v4
	v_add_u32_e32 v6, v6, v5
	s_waitcnt lgkmcnt(0)
	s_barrier
	ds_read_b32 v50, v3 offset:16640
	ds_read_b32 v51, v3 offset:16900
	ds_read_b32 v52, v3 offset:17160
	ds_read_b32 v53, v3 offset:17420
	ds_read_b32 v54, v3 offset:17680
	ds_read_b32 v55, v3 offset:17940
	ds_read_b32 v56, v3 offset:18200
	ds_read_b32 v57, v3 offset:18460
	s_waitcnt lgkmcnt(0)
	v_cvt_pk_bf16_f32 v60, v50, v51
	v_cvt_pk_bf16_f32 v61, v52, v53
	v_cvt_pk_bf16_f32 v62, v54, v55
	v_cvt_pk_bf16_f32 v63, v56, v57
	global_store_dwordx4 v6, v[60:63], s[26:27]
	s_add_u32 s7, s7, 1
	s_add_u32 s4, s4, 244
	s_cmp_lt_u32 s4, 0x800
	s_cbranch_scc0 .Lcvo_done
.Lcvo_j2:
	s_add_u32 s5, s4, 488
	s_cmp_lt_u32 s5, 0x800
	s_cbranch_scc0 .Lcvo_t2
	s_cmp_lt_u32 s5, 0x400
	s_cselect_b32 s20, 6, 4
	s_cselect_b32 s21, 14, 12
	s_cselect_b32 s26, s10, s12
	s_cselect_b32 s27, s11, s13
	s_and_b32 s22, s5, 0x3ff
	s_lshl_b32 s25, 1, s20
	s_sub_u32 s25, s25, 1
	s_and_b32 s24, s22, s25
	s_lshr_b32 s23, s22, s20
	s_lshl_b32 s23, s23, 6
	s_add_u32 s23, s23, s6
	s_lshl_b32 s23, s23, s21
	s_lshl_b32 s24, s24, 8
	s_add_u32 s23, s23, s24
	s_add_u32 s26, s26, s23
	s_addc_u32 s27, s27, 0
	s_add_u32 s25, s21, 3
	s_lshl_b32 s25, 1, s25
	v_add_u32_e32 v21, s25, v1
	v_add_u32_e32 v22, s25, v21
	v_add_u32_e32 v23, s25, v22
	v_add_u32_e32 v24, s25, v23
	v_add_u32_e32 v25, s25, v24
	v_add_u32_e32 v26, s25, v25
	v_add_u32_e32 v27, s25, v26
	global_load_dword v40, v1, s[26:27]
	global_load_dword v41, v21, s[26:27]
	global_load_dword v42, v22, s[26:27]
	global_load_dword v43, v23, s[26:27]
	global_load_dword v44, v24, s[26:27]
	global_load_dword v45, v25, s[26:27]
	global_load_dword v46, v26, s[26:27]
	global_load_dword v47, v27, s[26:27]
	s_cmp_lt_u32 s7, 2
	s_cbranch_scc1 .Lcvo_w2
	s_waitcnt vmcnt(18)
	s_branch .Lcvo_p2

; __device__ __forceinline__ unsigned cvt_pk_bf16(float lo, float hi) { unsigned r; asm volatile("v_cvt_pk_bf16_f32 %0, %1, %2" : "=v"(r) : "v"(lo), "v"(hi)); return r; }
; __device__ __forceinline__ void conv_matrix(const float* __restrict__ src, int K, int N, int Npad, bf16_t* __restrict__ dst, const float* __restrict__ scale, float* tile) {
;     ...
;     __syncthreads();
; #pragma unroll
;     for (int i = 0; i < 8; ++i) { tile[(ty + 8 * i) * 65 + tx] = va[i]; if (has1) tile[4160 + (ty + 8 * i) * 65 + tx] = vb[i]; }
;     __syncthreads();
;     { float v[8];
; #pragma unroll
;       for (int j = 0; j < 8; ++j) v[j] = tile[(ks + j) * 65 + nl];
;       u32x4 w = {cvt_pk_bf16(v[0], v[1]), cvt_pk_bf16(v[2], v[3]), cvt_pk_bf16(v[4], v[5]), cvt_pk_bf16(v[6], v[7])};
;       *(u32x4*)(dst + (size_t)(n0a + nl) * K + k0a + ks) = w; }
;     if (has1) { float v[8];
; #pragma unroll
;       for (int j = 0; j < 8; ++j) v[j] = tile[4160 + (ks + j) * 65 + nl];
;       u32x4 w = {cvt_pk_bf16(v[0], v[1]), cvt_pk_bf16(v[2], v[3]), cvt_pk_bf16(v[4], v[5]), cvt_pk_bf16(v[6], v[7])};
;       *(u32x4*)(dst + (size_t)(n0b + nl) * K + k0b + ks) = w; }
.Lcvo_p2:
	ds_write_b32 v2, v8 offset:33280
	ds_write_b32 v2, v9 offset:35360
	ds_write_b32 v2, v10 offset:37440
	ds_write_b32 v2, v11 offset:39520
	ds_write_b32 v2, v12 offset:41600
	ds_write_b32 v2, v13 offset:43680
	ds_write_b32 v2, v14 offset:45760
	ds_write_b32 v2, v15 offset:47840
	s_cmp_lt_u32 s4, 0x400
	s_cselect_b32 s20, 6, 4
	s_cselect_b32 s21, 17, 19
	s_cselect_b32 s8, 11, 13
	s_mov_b32 s9, 0x9280000
	s_cselect_b32 s9, 0x8a80000, s9
	s_and_b32 s22, s4, 0x3ff
	s_lshl_b32 s25, 1, s20
	s_sub_u32 s25, s25, 1
	s_and_b32 s24, s22, s25
	s_lshr_b32 s23, s22, s20
	s_lshl_b32 s24, s24, s21
	s_lshl_b32 s23, s23, 7
	s_add_u32 s24, s24, s23
	s_add_u32 s24, s24, s9
	s_add_u32 s26, s14, s24
	s_addc_u32 s27, s15, 0
	v_lshlrev_b32_e32 v6, s8, v4
	v_add_u32_e32 v6, v6, v5
	s_waitcnt lgkmcnt(0)
	s_barrier
	ds_read_b32 v50, v3 offset:33280
	ds_read_b32 v51, v3 offset:33540
	ds_read_b32 v52, v3 offset:33800
	ds_read_b32 v53, v3 offset:34060
	ds_read_b32 v54, v3 offset:34320
	ds_read_b32 v55, v3 offset:34580
	ds_read_b32 v56, v3 offset:34840
	ds_read_b32 v57, v3 offset:35100
	s_waitcnt lgkmcnt(0)
	v_cvt_pk_bf16_f32 v60, v50, v51
	v_cvt_pk_bf16_f32 v61, v52, v53
	v_cvt_pk_bf16_f32 v62, v54, v55
	v_cvt_pk_bf16_f32 v63, v56, v57
	global_store_dwordx4 v6, v[60:63], s[26:27]
	s_add_u32 s7, s7, 1
	s_add_u32 s4, s4, 244
	s_cmp_lt_u32 s4, 0x800
	s_cbranch_scc0 .Lcvo_done
	s_branch .Lcvo_j0

; __device__ __forceinline__ int tid_() { int t = threadIdx.x; asm volatile("" : "+v"(t)); return t; }
; __device__ __forceinline__ void conv_matrix(const float* __restrict__ src, int K, int N, int Npad, bf16_t* __restrict__ dst, const float* __restrict__ scale, float* tile) {
;   const int nk = K / 64, nn = Npad / 64, tot = nk * nn;
;   const int tid = tid_(), tx = tid & 63, ty = tid >> 6, nl = tid >> 3, ks = (tid & 7) * 8;
;   for (int i0 = blockIdx.x; i0 < tot; i0 += 2 * gridDim.x) {
;     const int i1 = i0 + gridDim.x; const bool has1 = i1 < tot;
;     const int k0a = (i0 % nk) * 64, n0a = (i0 / nk) * 64, k0b = has1 ? (i1 % nk) * 64 : 0, n0b = has1 ? (i1 / nk) * 64 : 0;
;     float va[8], vb[8];
; #pragma unroll
;     for (int i = 0; i < 8; ++i) { const int k = k0a + ty + 8 * i, n = n0a + tx; float v = (n < N) ? src[(size_t)k * N + n] : 0.f; if (scale) v *= scale[k]; va[i] = v; }
;     if (has1) {
; #pragma unroll
;       for (int i = 0; i < 8; ++i) { const int k = k0b + ty + 8 * i, n = n0b + tx; float v = (n < N) ? src[(size_t)k * N + n] : 0.f; if (scale) v *= scale[k]; vb[i] = v; }
;     }
.LBB0_2057:
	s_cmp_lt_u32 s2, 77
	s_cbranch_scc1 .Lcve_skip
	v_writelane_b32 v255, s4, 46
	v_writelane_b32 v255, s5, 47
	v_writelane_b32 v255, s10, 48
	v_writelane_b32 v255, s11, 49
	v_writelane_b32 v255, s12, 50
	v_writelane_b32 v255, s13, 51
	v_writelane_b32 v255, s14, 52
	v_writelane_b32 v255, s15, 53
	v_writelane_b32 v255, s20, 54
	v_writelane_b32 v255, s21, 55
	v_writelane_b32 v255, s22, 56
	v_writelane_b32 v255, s23, 57
	v_writelane_b32 v255, s24, 58
	v_writelane_b32 v255, s25, 59
	v_writelane_b32 v255, s26, 60
	v_writelane_b32 v255, s27, 61
	s_load_dwordx2 s[10:11], s[0:1], 0x40
	s_load_dwordx2 s[12:13], s[0:1], 0x48
	s_load_dwordx2 s[14:15], s[0:1], 0xd8
	v_and_b32_e32 v1, 63, v187
	v_lshrrev_b32_e32 v7, 6, v187
	v_lshrrev_b32_e32 v4, 3, v187
	v_and_b32_e32 v5, 7, v187
	s_nop 1
	v_readfirstlane_b32 s6, v7
	v_readlane_b32 s7, v255, 32
	v_mul_u32_u24_e32 v2, 0x41, v7
	v_add_u32_e32 v2, v2, v1
	v_lshlrev_b32_e32 v2, 2, v2
	v_add_u32_e32 v2, 16, v2
	v_lshlrev_b32_e32 v1, 2, v1
	v_mul_u32_u24_e32 v3, 0x208, v5
	v_add_u32_e32 v3, v3, v4
	v_lshlrev_b32_e32 v3, 2, v3
	v_add_u32_e32 v3, 16, v3
	v_lshlrev_b32_e32 v5, 4, v5
	s_lshl_b32 s7, s7, 24
	s_waitcnt lgkmcnt(0)
	s_add_u32 s10, s10, s7
	s_addc_u32 s11, s11, 0
	s_add_u32 s12, s12, s7
	s_addc_u32 s13, s13, 0
	s_sub_u32 s4, s2, 77
	s_cmp_lt_u32 s4, 0x400
	s_cselect_b32 s20, 6, 4
	s_cselect_b32 s21, 14, 12
	s_cselect_b32 s26, s10, s12
	s_cselect_b32 s27, s11, s13
	s_and_b32 s22, s4, 0x3ff
	s_lshl_b32 s25, 1, s20
	s_sub_u32 s25, s25, 1
	s_and_b32 s24, s22, s25
	s_lshr_b32 s23, s22, s20
	s_lshl_b32 s23, s23, 6
	s_add_u32 s23, s23, s6
	s_lshl_b32 s23, s23, s21
	s_lshl_b32 s24, s24, 8
	s_add_u32 s23, s23, s24
	s_add_u32 s26, s26, s23
	s_addc_u32 s27, s27, 0
	s_add_u32 s25, s21, 3
	s_lshl_b32 s25, 1, s25
	v_add_u32_e32 v21, s25, v1
	v_add_u32_e32 v22, s25, v21
	v_add_u32_e32 v23, s25, v22
	v_add_u32_e32 v24, s25, v23
	v_add_u32_e32 v25, s25, v24
	v_add_u32_e32 v26, s25, v25
	v_add_u32_e32 v27, s25, v26
	global_load_dword v30, v1, s[26:27]
	global_load_dword v31, v21, s[26:27]
	global_load_dword v32, v22, s[26:27]
	global_load_dword v33, v23, s[26:27]
	global_load_dword v34, v24, s[26:27]
	global_load_dword v35, v25, s[26:27]
	global_load_dword v36, v26, s[26:27]
	global_load_dword v37, v27, s[26:27]
	s_add_u32 s5, s4, 179
	s_cmp_lt_u32 s5, 0x400
	s_cselect_b32 s20, 6, 4
	s_cselect_b32 s21, 14, 12
	s_cselect_b32 s26, s10, s12
	s_cselect_b32 s27, s11, s13
	s_and_b32 s22, s5, 0x3ff
	s_lshl_b32 s25, 1, s20
	s_sub_u32 s25, s25, 1
	s_and_b32 s24, s22, s25
	s_lshr_b32 s23, s22, s20
	s_lshl_b32 s23, s23, 6
	s_add_u32 s23, s23, s6
	s_lshl_b32 s23, s23, s21
	s_lshl_b32 s24, s24, 8
	s_add_u32 s23, s23, s24
	s_add_u32 s26, s26, s23
	s_addc_u32 s27, s27, 0
	s_add_u32 s25, s21, 3
	s_lshl_b32 s25, 1, s25
	v_add_u32_e32 v21, s25, v1
	v_add_u32_e32 v22, s25, v21
	v_add_u32_e32 v23, s25, v22
	v_add_u32_e32 v24, s25, v23
	v_add_u32_e32 v25, s25, v24
	v_add_u32_e32 v26, s25, v25
	v_add_u32_e32 v27, s25, v26
	global_load_dword v40, v1, s[26:27]
	global_load_dword v41, v21, s[26:27]
	global_load_dword v42, v22, s[26:27]
	global_load_dword v43, v23, s[26:27]
	global_load_dword v44, v24, s[26:27]
	global_load_dword v45, v25, s[26:27]
	global_load_dword v46, v26, s[26:27]
	global_load_dword v47, v27, s[26:27]
	s_mov_b32 s7, 0
.Lcve_j0:
	s_add_u32 s5, s4, 358
	s_cmp_lt_u32 s5, 0x800
	s_cbranch_scc0 .Lcve_t0
	s_cmp_lt_u32 s5, 0x400
	s_cselect_b32 s20, 6, 4
	s_cselect_b32 s21, 14, 12
	s_cselect_b32 s26, s10, s12
	s_cselect_b32 s27, s11, s13
	s_and_b32 s22, s5, 0x3ff
	s_lshl_b32 s25, 1, s20
	s_sub_u32 s25, s25, 1
	s_and_b32 s24, s22, s25
	s_lshr_b32 s23, s22, s20
	s_lshl_b32 s23, s23, 6
	s_add_u32 s23, s23, s6
	s_lshl_b32 s23, s23, s21
	s_lshl_b32 s24, s24, 8
	s_add_u32 s23, s23, s24
	s_add_u32 s26, s26, s23
	s_addc_u32 s27, s27, 0
	s_add_u32 s25, s21, 3
	s_lshl_b32 s25, 1, s25
	v_add_u32_e32 v21, s25, v1
	v_add_u32_e32 v22, s25, v21
	v_add_u32_e32 v23, s25, v22
	v_add_u32_e32 v24, s25, v23
	v_add_u32_e32 v25, s25, v24
	v_add_u32_e32 v26, s25, v25
	v_add_u32_e32 v27, s25, v26
	global_load_dword v8, v1, s[26:27]
	global_load_dword v9, v21, s[26:27]
	global_load_dword v10, v22, s[26:27]
	global_load_dword v11, v23, s[26:27]
	global_load_dword v12, v24, s[26:27]
	global_load_dword v13, v25, s[26:27]
	global_load_dword v14, v26, s[26:27]
	global_load_dword v15, v27, s[26:27]
	s_cmp_lt_u32 s7, 2
	s_cbranch_scc1 .Lcve_w0
	s_waitcnt vmcnt(18)
	s_branch .Lcve_p0

; __device__ __forceinline__ unsigned cvt_pk_bf16(float lo, float hi) { unsigned r; asm volatile("v_cvt_pk_bf16_f32 %0, %1, %2" : "=v"(r) : "v"(lo), "v"(hi)); return r; }
; __device__ __forceinline__ void conv_matrix(const float* __restrict__ src, int K, int N, int Npad, bf16_t* __restrict__ dst, const float* __restrict__ scale, float* tile) {
;     ...
;   for (int i0 = blockIdx.x; i0 < tot; i0 += 2 * gridDim.x) {
;     const int i1 = i0 + gridDim.x; const bool has1 = i1 < tot;
;     const int k0a = (i0 % nk) * 64, n0a = (i0 / nk) * 64, k0b = has1 ? (i1 % nk) * 64 : 0, n0b = has1 ? (i1 / nk) * 64 : 0;
;     float va[8], vb[8];
; #pragma unroll
;     for (int i = 0; i < 8; ++i) { const int k = k0a + ty + 8 * i, n = n0a + tx; float v = (n < N) ? src[(size_t)k * N + n] : 0.f; if (scale) v *= scale[k]; va[i] = v; }
;     if (has1) {
; #pragma unroll
;       for (int i = 0; i < 8; ++i) { const int k = k0b + ty + 8 * i, n = n0b + tx; float v = (n < N) ? src[(size_t)k * N + n] : 0.f; if (scale) v *= scale[k]; vb[i] = v; }
;     }
;     __syncthreads();
; #pragma unroll
;     for (int i = 0; i < 8; ++i) { tile[(ty + 8 * i) * 65 + tx] = va[i]; if (has1) tile[4160 + (ty + 8 * i) * 65 + tx] = vb[i]; }
;     __syncthreads();
;     { float v[8];
; #pragma unroll
;       for (int j = 0; j < 8; ++j) v[j] = tile[(ks + j) * 65 + nl];
;       u32x4 w = {cvt_pk_bf16(v[0], v[1]), cvt_pk_bf16(v[2], v[3]), cvt_pk_bf16(v[4], v[5]), cvt_pk_bf16(v[6], v[7])};
;       *(u32x4*)(dst + (size_t)(n0a + nl) * K + k0a + ks) = w; }
;     if (has1) { float v[8];
; #pragma unroll
;       for (int j = 0; j < 8; ++j) v[j] = tile[4160 + (ks + j) * 65 + nl];
;       u32x4 w = {cvt_pk_bf16(v[0], v[1]), cvt_pk_bf16(v[2], v[3]), cvt_pk_bf16(v[4], v[5]), cvt_pk_bf16(v[6], v[7])};
;       *(u32x4*)(dst + (size_t)(n0b + nl) * K + k0b + ks) = w; }
.Lcve_p0:
	ds_write_b32 v2, v30 offset:0
	ds_write_b32 v2, v31 offset:2080
	ds_write_b32 v2, v32 offset:4160
	ds_write_b32 v2, v33 offset:6240
	ds_write_b32 v2, v34 offset:8320
	ds_write_b32 v2, v35 offset:10400
	ds_write_b32 v2, v36 offset:12480
	ds_write_b32 v2, v37 offset:14560
	s_cmp_lt_u32 s4, 0x400
	s_cselect_b32 s20, 6, 4
	s_cselect_b32 s21, 17, 19
	s_cselect_b32 s8, 11, 13
	s_mov_b32 s9, 0x9280000
	s_cselect_b32 s9, 0x8a80000, s9
	s_and_b32 s22, s4, 0x3ff
	s_lshl_b32 s25, 1, s20
	s_sub_u32 s25, s25, 1
	s_and_b32 s24, s22, s25
	s_lshr_b32 s23, s22, s20
	s_lshl_b32 s24, s24, s21
	s_lshl_b32 s23, s23, 7
	s_add_u32 s24, s24, s23
	s_add_u32 s24, s24, s9
	s_add_u32 s26, s14, s24
	s_addc_u32 s27, s15, 0
	v_lshlrev_b32_e32 v6, s8, v4
	v_add_u32_e32 v6, v6, v5
	s_waitcnt lgkmcnt(0)
	s_barrier
	ds_read_b32 v50, v3 offset:0
	ds_read_b32 v51, v3 offset:260
	ds_read_b32 v52, v3 offset:520
	ds_read_b32 v53, v3 offset:780
	ds_read_b32 v54, v3 offset:1040
	ds_read_b32 v55, v3 offset:1300
	ds_read_b32 v56, v3 offset:1560
	ds_read_b32 v57, v3 offset:1820
	s_waitcnt lgkmcnt(0)
	v_cvt_pk_bf16_f32 v60, v50, v51
	v_cvt_pk_bf16_f32 v61, v52, v53
	v_cvt_pk_bf16_f32 v62, v54, v55
	v_cvt_pk_bf16_f32 v63, v56, v57
	global_store_dwordx4 v6, v[60:63], s[26:27]
	s_add_u32 s7, s7, 1
	s_add_u32 s4, s4, 179
	s_cmp_lt_u32 s4, 0x800
	s_cbranch_scc0 .Lcve_done
.Lcve_j1:
	s_add_u32 s5, s4, 358
	s_cmp_lt_u32 s5, 0x800
	s_cbranch_scc0 .Lcve_t1
	s_cmp_lt_u32 s5, 0x400
	s_cselect_b32 s20, 6, 4
	s_cselect_b32 s21, 14, 12
	s_cselect_b32 s26, s10, s12
	s_cselect_b32 s27, s11, s13
	s_and_b32 s22, s5, 0x3ff
	s_lshl_b32 s25, 1, s20
	s_sub_u32 s25, s25, 1
	s_and_b32 s24, s22, s25
	s_lshr_b32 s23, s22, s20
	s_lshl_b32 s23, s23, 6
	s_add_u32 s23, s23, s6
	s_lshl_b32 s23, s23, s21
	s_lshl_b32 s24, s24, 8
	s_add_u32 s23, s23, s24
	s_add_u32 s26, s26, s23
	s_addc_u32 s27, s27, 0
	s_add_u32 s25, s21, 3
	s_lshl_b32 s25, 1, s25
	v_add_u32_e32 v21, s25, v1
	v_add_u32_e32 v22, s25, v21
	v_add_u32_e32 v23, s25, v22
	v_add_u32_e32 v24, s25, v23
	v_add_u32_e32 v25, s25, v24
	v_add_u32_e32 v26, s25, v25
	v_add_u32_e32 v27, s25, v26
	global_load_dword v30, v1, s[26:27]
	global_load_dword v31, v21, s[26:27]
	global_load_dword v32, v22, s[26:27]
	global_load_dword v33, v23, s[26:27]
	global_load_dword v34, v24, s[26:27]
	global_load_dword v35, v25, s[26:27]
	global_load_dword v36, v26, s[26:27]
	global_load_dword v37, v27, s[26:27]
	s_cmp_lt_u32 s7, 2
	s_cbranch_scc1 .Lcve_w1
	s_waitcnt vmcnt(18)
	s_branch .Lcve_p1

; __device__ __forceinline__ unsigned cvt_pk_bf16(float lo, float hi) { unsigned r; asm volatile("v_cvt_pk_bf16_f32 %0, %1, %2" : "=v"(r) : "v"(lo), "v"(hi)); return r; }
; __device__ __forceinline__ void conv_matrix(const float* __restrict__ src, int K, int N, int Npad, bf16_t* __restrict__ dst, const float* __restrict__ scale, float* tile) {
;     ...
;   for (int i0 = blockIdx.x; i0 < tot; i0 += 2 * gridDim.x) {
;     const int i1 = i0 + gridDim.x; const bool has1 = i1 < tot;
;     const int k0a = (i0 % nk) * 64, n0a = (i0 / nk) * 64, k0b = has1 ? (i1 % nk) * 64 : 0, n0b = has1 ? (i1 / nk) * 64 : 0;
;     float va[8], vb[8];
; #pragma unroll
;     for (int i = 0; i < 8; ++i) { const int k = k0a + ty + 8 * i, n = n0a + tx; float v = (n < N) ? src[(size_t)k * N + n] : 0.f; if (scale) v *= scale[k]; va[i] = v; }
;     if (has1) {
; #pragma unroll
;       for (int i = 0; i < 8; ++i) { const int k = k0b + ty + 8 * i, n = n0b + tx; float v = (n < N) ? src[(size_t)k * N + n] : 0.f; if (scale) v *= scale[k]; vb[i] = v; }
;     }
;     __syncthreads();
; #pragma unroll
;     for (int i = 0; i < 8; ++i) { tile[(ty + 8 * i) * 65 + tx] = va[i]; if (has1) tile[4160 + (ty + 8 * i) * 65 + tx] = vb[i]; }
;     __syncthreads();
;     { float v[8];
; #pragma unroll
;       for (int j = 0; j < 8; ++j) v[j] = tile[(ks + j) * 65 + nl];
;       u32x4 w = {cvt_pk_bf16(v[0], v[1]), cvt_pk_bf16(v[2], v[3]), cvt_pk_bf16(v[4], v[5]), cvt_pk_bf16(v[6], v[7])};
;       *(u32x4*)(dst + (size_t)(n0a + nl) * K + k0a + ks) = w; }
;     if (has1) { float v[8];
; #pragma unroll
;       for (int j = 0; j < 8; ++j) v[j] = tile[4160 + (ks + j) * 65 + nl];
;       u32x4 w = {cvt_pk_bf16(v[0], v[1]), cvt_pk_bf16(v[2], v[3]), cvt_pk_bf16(v[4], v[5]), cvt_pk_bf16(v[6], v[7])};
;       *(u32x4*)(dst + (size_t)(n0b + nl) * K + k0b + ks) = w; }
.Lcve_p1:
	ds_write_b32 v2, v40 offset:16640
	ds_write_b32 v2, v41 offset:18720
	ds_write_b32 v2, v42 offset:20800
	ds_write_b32 v2, v43 offset:22880
	ds_write_b32 v2, v44 offset:24960
	ds_write_b32 v2, v45 offset:27040
	ds_write_b32 v2, v46 offset:29120
	ds_write_b32 v2, v47 offset:31200
	s_cmp_lt_u32 s4, 0x400
	s_cselect_b32 s20, 6, 4
	s_cselect_b32 s21, 17, 19
	s_cselect_b32 s8, 11, 13
	s_mov_b32 s9, 0x9280000
	s_cselect_b32 s9, 0x8a80000, s9
	s_and_b32 s22, s4, 0x3ff
	s_lshl_b32 s25, 1, s20
	s_sub_u32 s25, s25, 1
	s_and_b32 s24, s22, s25
	s_lshr_b32 s23, s22, s20
	s_lshl_b32 s24, s24, s21
	s_lshl_b32 s23, s23, 7
	s_add_u32 s24, s24, s23
	s_add_u32 s24, s24, s9
	s_add_u32 s26, s14, s24
	s_addc_u32 s27, s15, 0
	v_lshlrev_b32_e32 v6, s8, v4
	v_add_u32_e32 v6, v6, v5
	s_waitcnt lgkmcnt(0)
	s_barrier
	ds_read_b32 v50, v3 offset:16640
	ds_read_b32 v51, v3 offset:16900
	ds_read_b32 v52, v3 offset:17160
	ds_read_b32 v53, v3 offset:17420
	ds_read_b32 v54, v3 offset:17680
	ds_read_b32 v55, v3 offset:17940
	ds_read_b32 v56, v3 offset:18200
	ds_read_b32 v57, v3 offset:18460
	s_waitcnt lgkmcnt(0)
	v_cvt_pk_bf16_f32 v60, v50, v51
	v_cvt_pk_bf16_f32 v61, v52, v53
	v_cvt_pk_bf16_f32 v62, v54, v55
	v_cvt_pk_bf16_f32 v63, v56, v57
	global_store_dwordx4 v6, v[60:63], s[26:27]
	s_add_u32 s7, s7, 1
	s_add_u32 s4, s4, 179
	s_cmp_lt_u32 s4, 0x800
	s_cbranch_scc0 .Lcve_done
.Lcve_j2:
	s_add_u32 s5, s4, 358
	s_cmp_lt_u32 s5, 0x800
	s_cbranch_scc0 .Lcve_t2
	s_cmp_lt_u32 s5, 0x400
	s_cselect_b32 s20, 6, 4
	s_cselect_b32 s21, 14, 12
	s_cselect_b32 s26, s10, s12
	s_cselect_b32 s27, s11, s13
	s_and_b32 s22, s5, 0x3ff
	s_lshl_b32 s25, 1, s20
	s_sub_u32 s25, s25, 1
	s_and_b32 s24, s22, s25
	s_lshr_b32 s23, s22, s20
	s_lshl_b32 s23, s23, 6
	s_add_u32 s23, s23, s6
	s_lshl_b32 s23, s23, s21
	s_lshl_b32 s24, s24, 8
	s_add_u32 s23, s23, s24
	s_add_u32 s26, s26, s23
	s_addc_u32 s27, s27, 0
	s_add_u32 s25, s21, 3
	s_lshl_b32 s25, 1, s25
	v_add_u32_e32 v21, s25, v1
	v_add_u32_e32 v22, s25, v21
	v_add_u32_e32 v23, s25, v22
	v_add_u32_e32 v24, s25, v23
	v_add_u32_e32 v25, s25, v24
	v_add_u32_e32 v26, s25, v25
	v_add_u32_e32 v27, s25, v26
	global_load_dword v40, v1, s[26:27]
	global_load_dword v41, v21, s[26:27]
	global_load_dword v42, v22, s[26:27]
	global_load_dword v43, v23, s[26:27]
	global_load_dword v44, v24, s[26:27]
	global_load_dword v45, v25, s[26:27]
	global_load_dword v46, v26, s[26:27]
	global_load_dword v47, v27, s[26:27]
	s_cmp_lt_u32 s7, 2
	s_cbranch_scc1 .Lcve_w2
	s_waitcnt vmcnt(18)
	s_branch .Lcve_p2

; __device__ __forceinline__ unsigned cvt_pk_bf16(float lo, float hi) { unsigned r; asm volatile("v_cvt_pk_bf16_f32 %0, %1, %2" : "=v"(r) : "v"(lo), "v"(hi)); return r; }
; __device__ __forceinline__ void conv_matrix(const float* __restrict__ src, int K, int N, int Npad, bf16_t* __restrict__ dst, const float* __restrict__ scale, float* tile) {
;     ...
;     __syncthreads();
; #pragma unroll
;     for (int i = 0; i < 8; ++i) { tile[(ty + 8 * i) * 65 + tx] = va[i]; if (has1) tile[4160 + (ty + 8 * i) * 65 + tx] = vb[i]; }
;     __syncthreads();
;     { float v[8];
; #pragma unroll
;       for (int j = 0; j < 8; ++j) v[j] = tile[(ks + j) * 65 + nl];
;       u32x4 w = {cvt_pk_bf16(v[0], v[1]), cvt_pk_bf16(v[2], v[3]), cvt_pk_bf16(v[4], v[5]), cvt_pk_bf16(v[6], v[7])};
;       *(u32x4*)(dst + (size_t)(n0a + nl) * K + k0a + ks) = w; }
;     if (has1) { float v[8];
; #pragma unroll
;       for (int j = 0; j < 8; ++j) v[j] = tile[4160 + (ks + j) * 65 + nl];
;       u32x4 w = {cvt_pk_bf16(v[0], v[1]), cvt_pk_bf16(v[2], v[3]), cvt_pk_bf16(v[4], v[5]), cvt_pk_bf16(v[6], v[7])};
;       *(u32x4*)(dst + (size_t)(n0b + nl) * K + k0b + ks) = w; }
.Lcve_p2:
	ds_write_b32 v2, v8 offset:33280
	ds_write_b32 v2, v9 offset:35360
	ds_write_b32 v2, v10 offset:37440
	ds_write_b32 v2, v11 offset:39520
	ds_write_b32 v2, v12 offset:41600
	ds_write_b32 v2, v13 offset:43680
	ds_write_b32 v2, v14 offset:45760
	ds_write_b32 v2, v15 offset:47840
	s_cmp_lt_u32 s4, 0x400
	s_cselect_b32 s20, 6, 4
	s_cselect_b32 s21, 17, 19
	s_cselect_b32 s8, 11, 13
	s_mov_b32 s9, 0x9280000
	s_cselect_b32 s9, 0x8a80000, s9
	s_and_b32 s22, s4, 0x3ff
	s_lshl_b32 s25, 1, s20
	s_sub_u32 s25, s25, 1
	s_and_b32 s24, s22, s25
	s_lshr_b32 s23, s22, s20
	s_lshl_b32 s24, s24, s21
	s_lshl_b32 s23, s23, 7
	s_add_u32 s24, s24, s23
	s_add_u32 s24, s24, s9
	s_add_u32 s26, s14, s24
	s_addc_u32 s27, s15, 0
	v_lshlrev_b32_e32 v6, s8, v4
	v_add_u32_e32 v6, v6, v5
	s_waitcnt lgkmcnt(0)
	s_barrier
	ds_read_b32 v50, v3 offset:33280
	ds_read_b32 v51, v3 offset:33540
	ds_read_b32 v52, v3 offset:33800
	ds_read_b32 v53, v3 offset:34060
	ds_read_b32 v54, v3 offset:34320
	ds_read_b32 v55, v3 offset:34580
	ds_read_b32 v56, v3 offset:34840
	ds_read_b32 v57, v3 offset:35100
	s_waitcnt lgkmcnt(0)
	v_cvt_pk_bf16_f32 v60, v50, v51
	v_cvt_pk_bf16_f32 v61, v52, v53
	v_cvt_pk_bf16_f32 v62, v54, v55
	v_cvt_pk_bf16_f32 v63, v56, v57
	global_store_dwordx4 v6, v[60:63], s[26:27]
	s_add_u32 s7, s7, 1
	s_add_u32 s4, s4, 179
	s_cmp_lt_u32 s4, 0x800
	s_cbranch_scc0 .Lcve_done
	s_branch .Lcve_j0
